# ALiBi bias and softmax reference folded into the QK accumulator init (one fmamk per score at step top; exp directly on the MFMA result)
# speedup vs baseline: 1.0095x; 1.0095x over previous
.LBB0_1380:
	v_mov_b32_e32 v248, s13
	ds_read2_b32 v[248:249], v248 offset0:1 offset1:129
	ds_read_b128 v[232:235], v222
	ds_read_b128 v[146:149], v222 offset:32
	ds_read_b128 v[236:239], v222 offset:8704
	ds_read_b128 v[150:153], v222 offset:8736
	ds_read_b128 v[154:157], v222 offset:64
	ds_read_b128 v[158:161], v222 offset:96
	ds_read_b128 v[162:165], v222 offset:8768
	ds_read_b128 v[228:231], v222 offset:8800
	v_add_u32_e32 v184, s12, v223
	v_add_u32_e32 v184, 0xc0, v184
	v_cvt_f32_i32_e32 v185, v184
	v_mul_f32_e64 v245, -v201, v185
	v_sub_f32_e32 v246, v245, v226
	v_mov_b32_e32 v82, v246
	v_fmamk_f32 v83, v201, 0x3f800000, v246
	v_fmamk_f32 v84, v201, 0x40000000, v246
	v_fmamk_f32 v85, v201, 0x40400000, v246
	v_fmamk_f32 v86, v201, 0x41000000, v246
	v_fmamk_f32 v87, v201, 0x41100000, v246
	v_fmamk_f32 v88, v201, 0x41200000, v246
	v_fmamk_f32 v89, v201, 0x41300000, v246
	v_fmamk_f32 v90, v201, 0x41800000, v246
	v_fmamk_f32 v91, v201, 0x41880000, v246
	v_fmamk_f32 v92, v201, 0x41900000, v246
	v_fmamk_f32 v93, v201, 0x41980000, v246
	v_fmamk_f32 v94, v201, 0x41c00000, v246
	v_fmamk_f32 v95, v201, 0x41c80000, v246
	v_fmamk_f32 v96, v201, 0x41d00000, v246
	v_fmamk_f32 v97, v201, 0x41d80000, v246
	v_fmamk_f32 v66, v201, 0x42000000, v246
	v_fmamk_f32 v67, v201, 0x42040000, v246
	v_fmamk_f32 v68, v201, 0x42080000, v246
	v_fmamk_f32 v69, v201, 0x420c0000, v246
	v_fmamk_f32 v70, v201, 0x42200000, v246
	v_fmamk_f32 v71, v201, 0x42240000, v246
	v_fmamk_f32 v72, v201, 0x42280000, v246
	v_fmamk_f32 v73, v201, 0x422c0000, v246
	v_fmamk_f32 v74, v201, 0x42400000, v246
	v_fmamk_f32 v75, v201, 0x42440000, v246
	v_fmamk_f32 v76, v201, 0x42480000, v246
	v_fmamk_f32 v77, v201, 0x424c0000, v246
	v_fmamk_f32 v78, v201, 0x42600000, v246
	v_fmamk_f32 v79, v201, 0x42640000, v246
	v_fmamk_f32 v80, v201, 0x42680000, v246
	v_fmamk_f32 v81, v201, 0x426c0000, v246
	s_add_i32 s46, s35, -1
	s_cmp_ge_i32 s46, s26
	s_cbranch_scc1 .LBB0_1384
	s_add_i32 s0, s12, s27
	s_addk_i32 s0, 0x140
	v_cvt_f32_i32_e32 v251, s0
	s_waitcnt lgkmcnt(8)
	v_mov_b32_e32 v252, v248
	v_mov_b32_e32 v250, v249
	v_pk_mul_f32 v[248:249], v[200:201], v[250:251]
	s_nop 0
	v_fma_f32 v250, v178, v252, -v249
	v_sub_f32_e32 v248, v248, v249
	v_cmp_lt_f32_e32 vcc, v250, v180
	v_cmp_lt_f32_e64 s[0:1], v248, v181
	s_and_b64 s[0:1], vcc, s[0:1]
	s_and_b64 vcc, exec, s[0:1]
	s_mov_b32 s0, s46
	s_cbranch_vccnz .LBB0_1383
	s_add_i32 s0, s6, 1
	s_ashr_i32 s1, s0, 31
	s_lshl_b64 s[0:1], s[0:1], 14
	v_lshl_add_u64 v[250:251], v[196:197], 0, s[0:1]
	v_add_co_u32_e32 v252, vcc, 0x2000, v250
	v_lshl_add_u64 v[248:249], v[198:199], 0, s[0:1]
	s_nop 0
	v_addc_co_u32_e32 v253, vcc, 0, v251, vcc
	global_load_dwordx4 v[98:101], v[250:251], off
	global_load_dwordx4 v[102:105], v[252:253], off
	global_load_dwordx4 v[106:109], v[248:249], off
	v_add_co_u32_e32 v248, vcc, 0x2000, v248
	s_mov_b32 s0, s26
	s_nop 0
	v_addc_co_u32_e32 v249, vcc, 0, v249, vcc
	global_load_dwordx4 v[110:113], v[248:249], off

.LBB0_1384:
	s_add_i32 s0, s34, -2
	s_cmp_lt_i32 s0, 1
	s_cbranch_scc1 .LBB0_1388
	s_waitcnt lgkmcnt(7)
	v_mfma_f32_32x32x16_bf16 v[82:97], v[232:235], v[130:133], v[82:97]
	s_waitcnt lgkmcnt(5)
	v_mfma_f32_32x32x16_bf16 v[66:81], v[236:239], v[130:133], v[66:81]
	v_mfma_f32_32x32x16_bf16 v[82:97], v[146:149], v[134:137], v[82:97]
	s_waitcnt lgkmcnt(4)
	v_mfma_f32_32x32x16_bf16 v[66:81], v[150:153], v[134:137], v[66:81]
	s_waitcnt lgkmcnt(3)
	v_mfma_f32_32x32x16_bf16 v[82:97], v[154:157], v[138:141], v[82:97]
	s_waitcnt lgkmcnt(1)
	v_mfma_f32_32x32x16_bf16 v[66:81], v[162:165], v[138:141], v[66:81]
	v_mfma_f32_32x32x16_bf16 v[82:97], v[158:161], v[142:145], v[82:97]
	ds_read_b128 v[162:165], v221 offset:17408
	ds_read_b128 v[146:149], v221 offset:17440
	ds_read_b128 v[166:169], v221 offset:22016
	ds_read_b128 v[150:153], v221 offset:22048
	ds_read_b128 v[170:173], v221 offset:26624
	ds_read_b128 v[154:157], v221 offset:26656
	ds_read_b128 v[174:177], v221 offset:31232
	ds_read_b128 v[158:161], v221 offset:31264
	s_waitcnt lgkmcnt(8)
	v_mfma_f32_32x32x16_bf16 v[66:81], v[228:231], v[142:145], v[66:81]
	ds_read_b128 v[228:231], v221 offset:26688
	ds_read_b128 v[232:235], v221 offset:26720
	ds_read_b128 v[236:239], v221 offset:31296
	ds_read_b128 v[240:243], v221 offset:31328
	s_nop 1
	v_exp_f32_e32 v82, v82
	v_exp_f32_e32 v83, v83
	v_exp_f32_e32 v84, v84
	v_exp_f32_e32 v85, v85
	v_exp_f32_e32 v86, v86
	v_add_f32_e32 v184, v82, v83
	v_exp_f32_e32 v87, v87
	v_add_f32_e32 v185, v84, v85
	v_exp_f32_e32 v88, v88
	v_exp_f32_e32 v89, v89
	v_exp_f32_e32 v90, v90
	v_add_f32_e32 v184, v184, v86
	v_exp_f32_e32 v91, v91
	v_add_f32_e32 v185, v185, v87
	v_exp_f32_e32 v92, v92
	v_add_f32_e32 v184, v184, v88
	v_exp_f32_e32 v93, v93
	v_add_f32_e32 v185, v185, v89
	v_exp_f32_e32 v94, v94
	v_add_f32_e32 v184, v184, v90
	v_exp_f32_e32 v95, v95
	v_add_f32_e32 v185, v185, v91
	v_exp_f32_e32 v96, v96
	v_add_f32_e32 v184, v184, v92
	v_exp_f32_e32 v97, v97
	v_add_f32_e32 v185, v185, v93
	v_add_f32_e32 v184, v184, v94
	v_add_f32_e32 v185, v185, v95
	v_add_f32_e32 v184, v184, v96
	v_add_f32_e32 v185, v185, v97
	v_add_f32_e32 v184, v184, v185
	v_add_f32_e32 v224, v224, v184
	v_cvt_pk_bf16_f32 v248, v82, v83
	v_cvt_pk_bf16_f32 v249, v84, v85
	v_cvt_pk_bf16_f32 v250, v86, v87
	v_cvt_pk_bf16_f32 v251, v88, v89
	v_cvt_pk_bf16_f32 v252, v90, v91
	v_cvt_pk_bf16_f32 v253, v92, v93
	v_cvt_pk_bf16_f32 v254, v94, v95
	v_cvt_pk_bf16_f32 v255, v96, v97
	ds_read_b128 v[82:85], v221 offset:17472
	ds_read_b128 v[86:89], v221 offset:17504
	ds_read_b128 v[90:93], v221 offset:22080
	ds_read_b128 v[94:97], v221 offset:22112
	s_waitcnt lgkmcnt(8)
	v_mfma_f32_32x32x16_bf16 v[50:65], v[162:165], v[248:251], v[50:65]
	v_exp_f32_e32 v66, v66
	v_exp_f32_e32 v67, v67
	v_exp_f32_e32 v68, v68
	v_exp_f32_e32 v69, v69
	v_exp_f32_e32 v70, v70
	v_mfma_f32_32x32x16_bf16 v[34:49], v[166:169], v[248:251], v[34:49]
	v_add_f32_e32 v188, v66, v67
	v_exp_f32_e32 v71, v71
	v_add_f32_e32 v227, v68, v69
	v_exp_f32_e32 v72, v72
	v_exp_f32_e32 v73, v73
	v_mfma_f32_32x32x16_bf16 v[18:33], v[170:173], v[248:251], v[18:33]
	v_exp_f32_e32 v74, v74
	v_add_f32_e32 v188, v188, v70
	v_exp_f32_e32 v75, v75
	v_add_f32_e32 v227, v227, v71
	v_exp_f32_e32 v76, v76
	v_mfma_f32_32x32x16_bf16 v[2:17], v[174:177], v[248:251], v[2:17]
	v_add_f32_e32 v188, v188, v72
	v_exp_f32_e32 v77, v77
	v_add_f32_e32 v227, v227, v73
	v_exp_f32_e32 v78, v78
	v_add_f32_e32 v188, v188, v74
	v_mfma_f32_32x32x16_bf16 v[50:65], v[146:149], v[252:255], v[50:65]
	v_exp_f32_e32 v79, v79
	v_add_f32_e32 v227, v227, v75
	v_exp_f32_e32 v80, v80
	v_add_f32_e32 v188, v188, v76
	v_exp_f32_e32 v81, v81
	v_mfma_f32_32x32x16_bf16 v[34:49], v[150:153], v[252:255], v[34:49]
	v_add_f32_e32 v227, v227, v77
	v_add_f32_e32 v188, v188, v78
	v_add_f32_e32 v227, v227, v79
	v_add_f32_e32 v188, v188, v80
	v_add_f32_e32 v227, v227, v81
	v_mfma_f32_32x32x16_bf16 v[18:33], v[154:157], v[252:255], v[18:33]
	v_add_f32_e32 v188, v188, v227
	v_add_f32_e32 v224, v224, v188
	v_cvt_pk_bf16_f32 v66, v66, v67
	v_cvt_pk_bf16_f32 v67, v68, v69
	v_cvt_pk_bf16_f32 v68, v70, v71
	v_mfma_f32_32x32x16_bf16 v[2:17], v[158:161], v[252:255], v[2:17]
	v_cvt_pk_bf16_f32 v69, v72, v73
	v_cvt_pk_bf16_f32 v70, v74, v75
	v_cvt_pk_bf16_f32 v71, v76, v77
	v_cvt_pk_bf16_f32 v72, v78, v79
	v_cvt_pk_bf16_f32 v73, v80, v81
	s_waitcnt lgkmcnt(0)
	s_nop 1
	v_mfma_f32_32x32x16_bf16 v[50:65], v[82:85], v[66:69], v[50:65]
	v_mfma_f32_32x32x16_bf16 v[34:49], v[90:93], v[66:69], v[34:49]
	v_mfma_f32_32x32x16_bf16 v[18:33], v[228:231], v[66:69], v[18:33]
	v_mfma_f32_32x32x16_bf16 v[2:17], v[236:239], v[66:69], v[2:17]
	v_mfma_f32_32x32x16_bf16 v[50:65], v[86:89], v[70:73], v[50:65]
	v_mfma_f32_32x32x16_bf16 v[34:49], v[94:97], v[70:73], v[34:49]
	v_mfma_f32_32x32x16_bf16 v[18:33], v[232:235], v[70:73], v[18:33]
	v_mfma_f32_32x32x16_bf16 v[2:17], v[240:243], v[70:73], v[2:17]

.LBB0_1390:
	s_andn2_b64 vcc, exec, s[0:1]
	s_waitcnt lgkmcnt(0)
	s_barrier
	s_cbranch_vccnz .LBB0_1396
	v_mov_b32_e32 v248, s13
	ds_read2st64_b32 v[248:249], v248 offset1:2
	ds_read_b128 v[232:235], v222 offset:35840
	ds_read_b128 v[146:149], v222 offset:35872
	ds_read_b128 v[236:239], v222 offset:44544
	ds_read_b128 v[150:153], v222 offset:44576
	ds_read_b128 v[154:157], v222 offset:35904
	ds_read_b128 v[158:161], v222 offset:35936
	ds_read_b128 v[162:165], v222 offset:44608
	ds_read_b128 v[228:231], v222 offset:44640
	v_add_u32_e32 v184, s12, v223
	v_add_u32_e32 v184, 0x100, v184
	v_cvt_f32_i32_e32 v185, v184
	v_mul_f32_e64 v245, -v201, v185
	v_sub_f32_e32 v246, v245, v226
	v_mov_b32_e32 v82, v246
	v_fmamk_f32 v83, v201, 0x3f800000, v246
	v_fmamk_f32 v84, v201, 0x40000000, v246
	v_fmamk_f32 v85, v201, 0x40400000, v246
	v_fmamk_f32 v86, v201, 0x41000000, v246
	v_fmamk_f32 v87, v201, 0x41100000, v246
	v_fmamk_f32 v88, v201, 0x41200000, v246
	v_fmamk_f32 v89, v201, 0x41300000, v246
	v_fmamk_f32 v90, v201, 0x41800000, v246
	v_fmamk_f32 v91, v201, 0x41880000, v246
	v_fmamk_f32 v92, v201, 0x41900000, v246
	v_fmamk_f32 v93, v201, 0x41980000, v246
	v_fmamk_f32 v94, v201, 0x41c00000, v246
	v_fmamk_f32 v95, v201, 0x41c80000, v246
	v_fmamk_f32 v96, v201, 0x41d00000, v246
	v_fmamk_f32 v97, v201, 0x41d80000, v246
	v_fmamk_f32 v66, v201, 0x42000000, v246
	v_fmamk_f32 v67, v201, 0x42040000, v246
	v_fmamk_f32 v68, v201, 0x42080000, v246
	v_fmamk_f32 v69, v201, 0x420c0000, v246
	v_fmamk_f32 v70, v201, 0x42200000, v246
	v_fmamk_f32 v71, v201, 0x42240000, v246
	v_fmamk_f32 v72, v201, 0x42280000, v246
	v_fmamk_f32 v73, v201, 0x422c0000, v246
	v_fmamk_f32 v74, v201, 0x42400000, v246
	v_fmamk_f32 v75, v201, 0x42440000, v246
	v_fmamk_f32 v76, v201, 0x42480000, v246
	v_fmamk_f32 v77, v201, 0x424c0000, v246
	v_fmamk_f32 v78, v201, 0x42600000, v246
	v_fmamk_f32 v79, v201, 0x42640000, v246
	v_fmamk_f32 v80, v201, 0x42680000, v246
	v_fmamk_f32 v81, v201, 0x426c0000, v246
	s_cmp_ge_i32 s35, s26
	s_cbranch_scc1 .LBB0_1397
	s_add_i32 s0, s12, s27
	s_addk_i32 s0, 0x180
	v_cvt_f32_i32_e32 v250, s0
	s_waitcnt lgkmcnt(8)
	v_mul_f32_e32 v252, v201, v250
	v_mov_b32_e32 v250, v248
	v_mov_b32_e32 v251, v249
	v_mov_b32_e32 v248, v252
	v_pk_fma_f32 v[248:249], v[178:179], v[250:251], v[248:249] op_sel_hi:[1,1,0] neg_lo:[0,0,1] neg_hi:[0,0,1]
	s_nop 0
	v_cmp_lt_f32_e32 vcc, v249, v181
	v_cmp_lt_f32_e64 s[0:1], v248, v180
	s_and_b64 s[0:1], s[0:1], vcc
	s_and_b64 vcc, exec, s[0:1]
	s_mov_b32 s0, s35
	s_cbranch_vccnz .LBB0_1394
	s_ashr_i32 s7, s6, 31
	s_lshl_b64 s[0:1], s[6:7], 14
	v_lshl_add_u64 v[250:251], v[196:197], 0, s[0:1]
	v_add_co_u32_e32 v252, vcc, 0x2000, v250
	v_lshl_add_u64 v[248:249], v[198:199], 0, s[0:1]
	s_nop 0
	v_addc_co_u32_e32 v253, vcc, 0, v251, vcc
	global_load_dwordx4 v[114:117], v[250:251], off
	global_load_dwordx4 v[118:121], v[252:253], off
	global_load_dwordx4 v[122:125], v[248:249], off
	v_add_co_u32_e32 v248, vcc, 0x2000, v248
	s_mov_b32 s0, s26
	s_nop 0
	v_addc_co_u32_e32 v249, vcc, 0, v249, vcc
	global_load_dwordx4 v[126:129], v[248:249], off

.LBB0_1398:
	s_waitcnt lgkmcnt(7)
	v_mfma_f32_32x32x16_bf16 v[82:97], v[232:235], v[130:133], v[82:97]
	s_waitcnt lgkmcnt(5)
	v_mfma_f32_32x32x16_bf16 v[66:81], v[236:239], v[130:133], v[66:81]
	v_mfma_f32_32x32x16_bf16 v[82:97], v[146:149], v[134:137], v[82:97]
	s_waitcnt lgkmcnt(4)
	v_mfma_f32_32x32x16_bf16 v[66:81], v[150:153], v[134:137], v[66:81]
	s_waitcnt lgkmcnt(3)
	v_mfma_f32_32x32x16_bf16 v[82:97], v[154:157], v[138:141], v[82:97]
	s_waitcnt lgkmcnt(1)
	v_mfma_f32_32x32x16_bf16 v[66:81], v[162:165], v[138:141], v[66:81]
	v_mfma_f32_32x32x16_bf16 v[82:97], v[158:161], v[142:145], v[82:97]
	ds_read_b128 v[166:169], v221 offset:53248
	ds_read_b128 v[150:153], v221 offset:53280
	ds_read_b128 v[162:165], v225 offset:13824
	ds_read_b128 v[146:149], v225 offset:13856
	ds_read_b128 v[170:173], v221 offset:57856
	ds_read_b128 v[154:157], v221 offset:57888
	ds_read_b128 v[174:177], v221 offset:62464
	ds_read_b128 v[158:161], v221 offset:62496
	s_waitcnt lgkmcnt(8)
	v_mfma_f32_32x32x16_bf16 v[66:81], v[228:231], v[142:145], v[66:81]
	ds_read_b128 v[228:231], v221 offset:62528
	ds_read_b128 v[232:235], v221 offset:62560
	ds_read_b128 v[236:239], v225 offset:13888
	ds_read_b128 v[240:243], v225 offset:13920
	s_nop 1
	v_exp_f32_e32 v82, v82
	v_exp_f32_e32 v83, v83
	v_exp_f32_e32 v84, v84
	v_exp_f32_e32 v85, v85
	v_exp_f32_e32 v86, v86
	v_add_f32_e32 v184, v82, v83
	v_exp_f32_e32 v87, v87
	v_add_f32_e32 v185, v84, v85
	v_exp_f32_e32 v88, v88
	v_exp_f32_e32 v89, v89
	v_exp_f32_e32 v90, v90
	v_add_f32_e32 v184, v184, v86
	v_exp_f32_e32 v91, v91
	v_add_f32_e32 v185, v185, v87
	v_exp_f32_e32 v92, v92
	v_add_f32_e32 v184, v184, v88
	v_exp_f32_e32 v93, v93
	v_add_f32_e32 v185, v185, v89
	v_exp_f32_e32 v94, v94
	v_add_f32_e32 v184, v184, v90
	v_exp_f32_e32 v95, v95
	v_add_f32_e32 v185, v185, v91
	v_exp_f32_e32 v96, v96
	v_add_f32_e32 v184, v184, v92
	v_exp_f32_e32 v97, v97
	v_add_f32_e32 v185, v185, v93
	v_add_f32_e32 v184, v184, v94
	v_add_f32_e32 v185, v185, v95
	v_add_f32_e32 v184, v184, v96
	v_add_f32_e32 v185, v185, v97
	v_add_f32_e32 v184, v184, v185
	v_add_f32_e32 v224, v224, v184
	v_cvt_pk_bf16_f32 v248, v82, v83
	v_cvt_pk_bf16_f32 v249, v84, v85
	v_cvt_pk_bf16_f32 v250, v86, v87
	v_cvt_pk_bf16_f32 v251, v88, v89
	v_cvt_pk_bf16_f32 v252, v90, v91
	v_cvt_pk_bf16_f32 v253, v92, v93
	v_cvt_pk_bf16_f32 v254, v94, v95
	v_cvt_pk_bf16_f32 v255, v96, v97
	ds_read_b128 v[82:85], v221 offset:53312
	ds_read_b128 v[86:89], v221 offset:53344
	ds_read_b128 v[90:93], v221 offset:57920
	ds_read_b128 v[94:97], v221 offset:57952
	s_waitcnt lgkmcnt(8)
	v_mfma_f32_32x32x16_bf16 v[50:65], v[166:169], v[248:251], v[50:65]
	v_exp_f32_e32 v66, v66
	v_exp_f32_e32 v67, v67
	v_exp_f32_e32 v68, v68
	v_exp_f32_e32 v69, v69
	v_exp_f32_e32 v70, v70
	v_mfma_f32_32x32x16_bf16 v[34:49], v[170:173], v[248:251], v[34:49]
	v_add_f32_e32 v188, v66, v67
	v_exp_f32_e32 v71, v71
	v_add_f32_e32 v227, v68, v69
	v_exp_f32_e32 v72, v72
	v_exp_f32_e32 v73, v73
	v_mfma_f32_32x32x16_bf16 v[18:33], v[174:177], v[248:251], v[18:33]
	v_exp_f32_e32 v74, v74
	v_add_f32_e32 v188, v188, v70
	v_exp_f32_e32 v75, v75
	v_add_f32_e32 v227, v227, v71
	v_exp_f32_e32 v76, v76
	v_mfma_f32_32x32x16_bf16 v[2:17], v[162:165], v[248:251], v[2:17]
	v_add_f32_e32 v188, v188, v72
	v_exp_f32_e32 v77, v77
	v_add_f32_e32 v227, v227, v73
	v_exp_f32_e32 v78, v78
	v_add_f32_e32 v188, v188, v74
	v_mfma_f32_32x32x16_bf16 v[50:65], v[150:153], v[252:255], v[50:65]
	v_exp_f32_e32 v79, v79
	v_add_f32_e32 v227, v227, v75
	v_exp_f32_e32 v80, v80
	v_add_f32_e32 v188, v188, v76
	v_exp_f32_e32 v81, v81
	v_mfma_f32_32x32x16_bf16 v[34:49], v[154:157], v[252:255], v[34:49]
	v_add_f32_e32 v227, v227, v77
	v_add_f32_e32 v188, v188, v78
	v_add_f32_e32 v227, v227, v79
	v_add_f32_e32 v188, v188, v80
	v_add_f32_e32 v227, v227, v81
	v_mfma_f32_32x32x16_bf16 v[18:33], v[158:161], v[252:255], v[18:33]
	v_add_f32_e32 v188, v188, v227
	v_add_f32_e32 v224, v224, v188
	v_cvt_pk_bf16_f32 v66, v66, v67
	v_cvt_pk_bf16_f32 v67, v68, v69
	v_cvt_pk_bf16_f32 v68, v70, v71
	v_mfma_f32_32x32x16_bf16 v[2:17], v[146:149], v[252:255], v[2:17]
	v_cvt_pk_bf16_f32 v69, v72, v73
	v_cvt_pk_bf16_f32 v70, v74, v75
	v_cvt_pk_bf16_f32 v71, v76, v77
	v_cvt_pk_bf16_f32 v72, v78, v79
	v_cvt_pk_bf16_f32 v73, v80, v81
	s_waitcnt lgkmcnt(0)
	s_nop 1
	v_mfma_f32_32x32x16_bf16 v[50:65], v[82:85], v[66:69], v[50:65]
	v_mfma_f32_32x32x16_bf16 v[34:49], v[90:93], v[66:69], v[34:49]
	v_mfma_f32_32x32x16_bf16 v[18:33], v[228:231], v[66:69], v[18:33]
	v_mfma_f32_32x32x16_bf16 v[2:17], v[236:239], v[66:69], v[2:17]
	v_mfma_f32_32x32x16_bf16 v[50:65], v[86:89], v[70:73], v[50:65]
	v_mfma_f32_32x32x16_bf16 v[34:49], v[94:97], v[70:73], v[34:49]
	v_mfma_f32_32x32x16_bf16 v[18:33], v[232:235], v[70:73], v[18:33]
	v_mfma_f32_32x32x16_bf16 v[2:17], v[240:243], v[70:73], v[2:17]
	s_cmp_ge_i32 s46, s26
	s_cbranch_scc1 .LBB0_1379
